# attention step A: four V fragments prefetched during the QK chain into free registers; waits moved to first consumer
# baseline (speedup 1.0000x reference)
.LBB0_182:
	ds_read_b128 v[96:99], v169 offset:13312
	ds_read_b128 v[232:235], v169 offset:19968
	v_exp_f32_e32 v32, v32
	v_exp_f32_e32 v33, v33
	v_exp_f32_e32 v34, v34
	v_exp_f32_e32 v35, v35
	v_exp_f32_e32 v36, v36
	v_exp_f32_e32 v37, v37
	v_exp_f32_e32 v38, v38
	s_waitcnt lgkmcnt(1)
	v_mfma_f32_32x32x16_bf16 v[80:95], v[96:99], v[116:119], v[48:63]
	ds_read_b128 v[100:103], v169 offset:13344
	ds_read_b128 v[236:239], v169 offset:20000
	v_exp_f32_e32 v39, v39
	v_exp_f32_e32 v40, v40
	v_exp_f32_e32 v41, v41
	v_exp_f32_e32 v42, v42
	v_exp_f32_e32 v43, v43
	v_exp_f32_e32 v44, v44
	s_waitcnt lgkmcnt(1)
	v_mfma_f32_32x32x16_bf16 v[80:95], v[100:103], v[120:123], v[80:95]
	ds_read_b128 v[96:99], v169 offset:13376
	ds_read_b128 v[240:243], v169 offset:20032
	ds_read_b128 v[64:67], v229 offset:31264
	v_exp_f32_e32 v45, v45
	v_exp_f32_e32 v46, v46
	v_exp_f32_e32 v47, v47
	v_exp_f32_e32 v182, v182
	v_exp_f32_e32 v183, v183
	s_waitcnt lgkmcnt(2)
	v_mfma_f32_32x32x16_bf16 v[80:95], v[96:99], v[124:127], v[80:95]
	ds_read_b128 v[96:99], v169 offset:13408
	ds_read_b128 v[244:247], v169 offset:20064
	ds_read_b128 v[68:71], v229 offset:26688
	v_exp_f32_e32 v184, v184
	v_exp_f32_e32 v185, v185
	v_exp_f32_e32 v186, v186
	v_exp_f32_e32 v187, v187
	v_exp_f32_e32 v188, v188
	s_waitcnt lgkmcnt(2)
	v_mfma_f32_32x32x16_bf16 v[80:95], v[96:99], v[128:131], v[80:95]
	ds_read_b128 v[96:99], v169 offset:13440
	ds_read_b128 v[248:251], v169 offset:20096
	ds_read_b128 v[72:75], v229 offset:26720
	v_exp_f32_e32 v189, v189
	v_exp_f32_e32 v190, v190
	v_exp_f32_e32 v191, v191
	v_exp_f32_e32 v192, v192
	v_exp_f32_e32 v193, v193
	s_waitcnt lgkmcnt(2)
	v_mfma_f32_32x32x16_bf16 v[80:95], v[96:99], v[132:135], v[80:95]
	ds_read_b128 v[96:99], v169 offset:13472
	ds_read_b128 v[148:151], v169 offset:20128
	ds_read_b128 v[76:79], v229 offset:31328
	v_exp_f32_e32 v194, v194
	v_exp_f32_e32 v195, v195
	v_exp_f32_e32 v196, v196
	v_exp_f32_e32 v197, v197
	s_andn2_b64 vcc, exec, s[28:29]
	s_waitcnt lgkmcnt(2)
	v_mfma_f32_32x32x16_bf16 v[80:95], v[96:99], v[136:139], v[80:95]
	v_mfma_f32_32x32x16_bf16 v[96:111], v[232:235], v[116:119], v[48:63]
	v_cvt_pk_bf16_f32 v232, v32, v33
	v_cvt_pk_bf16_f32 v233, v34, v35
	v_cvt_pk_bf16_f32 v234, v36, v37
	v_cvt_pk_bf16_f32 v235, v38, v39
	v_mfma_f32_32x32x16_bf16 v[96:111], v[236:239], v[120:123], v[96:111]
	ds_read_b128 v[236:239], v229 offset:31232
	v_mfma_f32_32x32x16_bf16 v[96:111], v[240:243], v[124:127], v[96:111]
	ds_read_b128 v[240:243], v229 offset:26624
	v_mfma_f32_32x32x16_bf16 v[96:111], v[244:247], v[128:131], v[96:111]
	ds_read_b128 v[244:247], v229 offset:26656
	v_mfma_f32_32x32x16_bf16 v[96:111], v[248:251], v[132:135], v[96:111]
	s_waitcnt lgkmcnt(1)
	v_mfma_f32_32x32x16_bf16 v[0:15], v[232:235], v[240:243], v[0:15]
	ds_read_b128 v[240:243], v229 offset:31296
	v_mfma_f32_32x32x16_bf16 v[16:31], v[232:235], v[236:239], v[16:31]
	v_cvt_pk_bf16_f32 v232, v40, v41
	v_cvt_pk_bf16_f32 v233, v42, v43
	v_cvt_pk_bf16_f32 v234, v44, v45
	v_cvt_pk_bf16_f32 v235, v46, v47
	s_waitcnt lgkmcnt(1)
	s_nop 0
	v_mfma_f32_32x32x16_bf16 v[0:15], v[232:235], v[244:247], v[0:15]
	v_mfma_f32_32x32x16_bf16 v[16:31], v[232:235], v[64:67], v[16:31]
	v_cvt_pk_bf16_f32 v232, v182, v183
	v_cvt_pk_bf16_f32 v233, v184, v185
	v_cvt_pk_bf16_f32 v234, v186, v187
	v_cvt_pk_bf16_f32 v235, v188, v189
	s_nop 1
	v_mfma_f32_32x32x16_bf16 v[0:15], v[232:235], v[68:71], v[0:15]
	s_waitcnt lgkmcnt(0)
	v_mfma_f32_32x32x16_bf16 v[16:31], v[232:235], v[240:243], v[16:31]
	v_cvt_pk_bf16_f32 v232, v190, v191
	v_cvt_pk_bf16_f32 v233, v192, v193
	v_cvt_pk_bf16_f32 v234, v194, v195
	v_cvt_pk_bf16_f32 v235, v196, v197
	s_waitcnt lgkmcnt(0)
	s_barrier
	v_mfma_f32_32x32x16_bf16 v[0:15], v[232:235], v[72:75], v[0:15]
	v_mfma_f32_32x32x16_bf16 v[96:111], v[148:151], v[136:139], v[96:111]
	v_cndmask_b32_e64 v148, 0, 1, s[28:29]
	v_cmp_ne_u32_e64 s[12:13], 1, v148
	v_mfma_f32_32x32x16_bf16 v[16:31], v[232:235], v[76:79], v[16:31]
	s_cbranch_vccz .LBB0_190
	s_and_b64 vcc, exec, s[10:11]
	s_cbranch_vccz .LBB0_193
